# v35 + mLSTM-out causal QK^T strip: the 8 K fragments of a k-step read together (one LDS wait per k-step instead of one per block)
# speedup vs baseline: 1.0004x; 1.0004x over previous
.LBB0_631:
	s_or_b64 exec, exec, s[2:3]
	s_ashr_i32 s37, s9, 6
	v_and_b32_e32 v60, 15, v106
	s_lshl_b32 s34, s37, 4
	v_or_b32_e32 v72, s34, v60
	v_add_u32_e32 v0, s8, v72
	s_waitcnt lgkmcnt(0)
	v_mov_b64_e32 v[2:3], s[4:5]
	v_lshrrev_b32_e32 v61, 4, v191
	v_mad_i64_i32 v[2:3], s[2:3], v0, s49, v[2:3]
	v_lshl_add_u64 v[2:3], v[108:109], 1, v[2:3]
	v_lshlrev_b32_e32 v0, 3, v61
	v_lshl_add_u64 v[38:39], v[2:3], 0, v[0:1]
	global_load_dwordx2 v[54:55], v[38:39], off offset:1024
	global_load_dwordx2 v[52:53], v[38:39], off offset:1056
	global_load_dwordx2 v[50:51], v[38:39], off offset:1088
	global_load_dwordx2 v[48:49], v[38:39], off offset:1120
	global_load_dwordx2 v[46:47], v[38:39], off offset:1152
	global_load_dwordx2 v[44:45], v[38:39], off offset:1184
	global_load_dwordx2 v[42:43], v[38:39], off offset:1216
	global_load_dwordx2 v[40:41], v[38:39], off offset:1248
	v_lshl_add_u32 v57, v72, 2, 0
	v_bitop3_b32 v3, v61, v106, 15 bitop3:0x78
	v_add_u32_e32 v2, 0x20200, v57
	v_lshl_add_u32 v62, v72, 8, 0
	v_lshlrev_b32_e32 v64, 4, v3
	v_add_u32_e32 v65, v62, v64
	ds_read_b32 v59, v2
	ds_read_b128 v[18:21], v65
	v_lshlrev_b32_e32 v63, 8, v60
	v_add_u32_e32 v58, 0, v63
	s_cmp_gt_i32 s37, -1
	s_cselect_b64 s[4:5], -1, 0
	s_cmp_lt_i32 s37, 0
	v_add_u32_e32 v34, v58, v64
	ds_read_b128 v[120:123], v34 offset:32768
	ds_read_b128 v[124:127], v34 offset:36864
	ds_read_b128 v[128:131], v34 offset:40960
	ds_read_b128 v[132:135], v34 offset:45056
	ds_read_b128 v[136:139], v34 offset:49152
	ds_read_b128 v[140:143], v34 offset:53248
	ds_read_b128 v[144:147], v34 offset:57344
	ds_read_b128 v[148:151], v34 offset:61440
	s_waitcnt lgkmcnt(0)
	s_cbranch_scc1 .LBB0_640
	v_mfma_f32_16x16x32_bf16 v[2:5], v[120:123], v[18:21], 0
	s_cmp_gt_i32 s37, 0
	s_cselect_b64 s[6:7], -1, 0
	s_cmp_lt_i32 s37, 1
	s_cbranch_scc1 .LBB0_641
.LBB0_633:
	v_mfma_f32_16x16x32_bf16 v[6:9], v[124:127], v[18:21], 0
	s_cmp_gt_i32 s37, 1
	s_cselect_b64 s[8:9], -1, 0
	s_cmp_lt_i32 s37, 2
	s_cbranch_scc1 .LBB0_642
.LBB0_634:
	v_mfma_f32_16x16x32_bf16 v[10:13], v[128:131], v[18:21], 0
	s_cmp_gt_i32 s37, 2
	s_cselect_b64 s[10:11], -1, 0
	s_cmp_lt_i32 s37, 3
	s_cbranch_scc0 .LBB0_643

.LBB0_643:
	v_mfma_f32_16x16x32_bf16 v[14:17], v[132:135], v[18:21], 0
	s_cmp_gt_i32 s37, 3
	s_cselect_b64 s[12:13], -1, 0
	s_cmp_lt_i32 s37, 4
	s_cbranch_scc1 .LBB0_636
.LBB0_644:
	v_mfma_f32_16x16x32_bf16 v[22:25], v[136:139], v[18:21], 0
	s_cmp_gt_i32 s37, 4
	s_cselect_b64 s[14:15], -1, 0
	s_cmp_lt_i32 s37, 5
	s_cbranch_scc1 .LBB0_637
.LBB0_645:
	v_mfma_f32_16x16x32_bf16 v[26:29], v[140:143], v[18:21], 0
	s_cmp_gt_i32 s37, 5
	s_cselect_b64 s[16:17], -1, 0
	s_cmp_lt_i32 s37, 6
	s_cbranch_scc1 .LBB0_638
.LBB0_646:
	v_mfma_f32_16x16x32_bf16 v[30:33], v[144:147], v[18:21], 0
	s_cmp_gt_i32 s37, 6
	s_cselect_b64 s[28:29], -1, 0
	s_cmp_lt_i32 s37, 7
	s_cbranch_scc1 .LBB0_639
.LBB0_647:
	v_mfma_f32_16x16x32_bf16 v[18:21], v[148:151], v[18:21], 0
.LBB0_648:
	v_bitop3_b32 v34, v61, v60, 4 bitop3:0x36
	v_lshlrev_b32_e32 v66, 4, v34
	v_add_u32_e32 v70, v62, v66
	ds_read_b128 v[34:37], v70
	v_cndmask_b32_e64 v67, 0, 1, s[4:5]
	v_cmp_ne_u32_e64 s[2:3], 1, v67
	s_andn2_b64 vcc, exec, s[4:5]
	v_add_u32_e32 v67, v58, v66
	ds_read_b128 v[120:123], v67 offset:32768
	ds_read_b128 v[124:127], v67 offset:36864
	ds_read_b128 v[128:131], v67 offset:40960
	ds_read_b128 v[132:135], v67 offset:45056
	ds_read_b128 v[136:139], v67 offset:49152
	ds_read_b128 v[140:143], v67 offset:53248
	ds_read_b128 v[144:147], v67 offset:57344
	ds_read_b128 v[148:151], v67 offset:61440
	s_waitcnt lgkmcnt(0)
	s_cbranch_vccnz .LBB0_650
	v_mfma_f32_16x16x32_bf16 v[2:5], v[120:123], v[34:37], v[2:5]
.LBB0_650:
	v_cndmask_b32_e64 v68, 0, 1, s[6:7]
	v_cmp_ne_u32_e64 s[4:5], 1, v68
	s_andn2_b64 vcc, exec, s[6:7]
	s_cbranch_vccnz .LBB0_652
	v_mfma_f32_16x16x32_bf16 v[6:9], v[124:127], v[34:37], v[6:9]

.LBB0_658:
	v_mfma_f32_16x16x32_bf16 v[18:21], v[148:151], v[34:37], v[18:21]
.LBB0_659:
	s_waitcnt lgkmcnt(0)
	v_bitop3_b32 v34, v61, v60, 8 bitop3:0x36
	v_lshlrev_b32_e32 v68, 4, v34
	v_add_u32_e32 v69, v62, v68
	ds_read_b128 v[34:37], v69
	s_and_b64 vcc, exec, s[2:3]
	v_add_u32_e32 v67, v58, v68
	ds_read_b128 v[120:123], v67 offset:32768
	ds_read_b128 v[124:127], v67 offset:36864
	ds_read_b128 v[128:131], v67 offset:40960
	ds_read_b128 v[132:135], v67 offset:45056
	ds_read_b128 v[136:139], v67 offset:49152
	ds_read_b128 v[140:143], v67 offset:53248
	ds_read_b128 v[144:147], v67 offset:57344
	ds_read_b128 v[148:151], v67 offset:61440
	s_waitcnt lgkmcnt(0)
	s_cbranch_vccnz .LBB0_661
	v_mfma_f32_16x16x32_bf16 v[2:5], v[120:123], v[34:37], v[2:5]
.LBB0_661:
	s_and_b64 vcc, exec, s[4:5]
	s_cbranch_vccnz .LBB0_663
	v_mfma_f32_16x16x32_bf16 v[6:9], v[124:127], v[34:37], v[6:9]

.LBB0_670:
	s_waitcnt lgkmcnt(0)
	v_bitop3_b32 v34, v61, v60, 12 bitop3:0x36
	v_lshlrev_b32_e32 v67, 4, v34
	v_add_u32_e32 v71, v62, v67
	ds_read_b128 v[34:37], v71
	s_and_b64 vcc, exec, s[2:3]
	v_add_u32_e32 v58, v58, v67
	ds_read_b128 v[120:123], v58 offset:32768
	ds_read_b128 v[124:127], v58 offset:36864
	ds_read_b128 v[128:131], v58 offset:40960
	ds_read_b128 v[132:135], v58 offset:45056
	ds_read_b128 v[136:139], v58 offset:49152
	ds_read_b128 v[140:143], v58 offset:53248
	ds_read_b128 v[144:147], v58 offset:57344
	ds_read_b128 v[148:151], v58 offset:61440
	s_waitcnt lgkmcnt(0)
	s_cbranch_vccnz .LBB0_672
	v_mfma_f32_16x16x32_bf16 v[2:5], v[120:123], v[34:37], v[2:5]

.LBB0_748:
	v_mfma_f32_16x16x32_bf16 v[10:13], v[128:131], v[34:37], v[10:13]
	v_cndmask_b32_e64 v68, 0, 1, s[10:11]
	v_cmp_ne_u32_e64 s[8:9], 1, v68
	s_andn2_b64 vcc, exec, s[10:11]
	s_cbranch_vccnz .LBB0_654
.LBB0_749:
	v_mfma_f32_16x16x32_bf16 v[14:17], v[132:135], v[34:37], v[14:17]
	v_cndmask_b32_e64 v68, 0, 1, s[12:13]
	v_cmp_ne_u32_e64 s[10:11], 1, v68
	s_andn2_b64 vcc, exec, s[12:13]
	s_cbranch_vccnz .LBB0_655
.LBB0_750:
	v_mfma_f32_16x16x32_bf16 v[22:25], v[136:139], v[34:37], v[22:25]
	v_cndmask_b32_e64 v68, 0, 1, s[14:15]
	v_cmp_ne_u32_e64 s[12:13], 1, v68
	s_andn2_b64 vcc, exec, s[14:15]
	s_cbranch_vccnz .LBB0_656
.LBB0_751:
	v_mfma_f32_16x16x32_bf16 v[26:29], v[140:143], v[34:37], v[26:29]
	v_cndmask_b32_e64 v68, 0, 1, s[16:17]
	v_cmp_ne_u32_e64 s[14:15], 1, v68
	s_andn2_b64 vcc, exec, s[16:17]
	s_cbranch_vccnz .LBB0_657
.LBB0_752:
	v_mfma_f32_16x16x32_bf16 v[30:33], v[144:147], v[34:37], v[30:33]
	v_cndmask_b32_e64 v68, 0, 1, s[28:29]
	v_cmp_ne_u32_e64 s[16:17], 1, v68
	s_andn2_b64 vcc, exec, s[28:29]
	s_cbranch_vccz .LBB0_658
	s_branch .LBB0_659
.LBB0_753:
	v_mfma_f32_16x16x32_bf16 v[10:13], v[128:131], v[34:37], v[10:13]
	s_and_b64 vcc, exec, s[8:9]
	s_cbranch_vccnz .LBB0_665
.LBB0_754:
	v_mfma_f32_16x16x32_bf16 v[14:17], v[132:135], v[34:37], v[14:17]
	s_and_b64 vcc, exec, s[10:11]
	s_cbranch_vccnz .LBB0_666
.LBB0_755:
	v_mfma_f32_16x16x32_bf16 v[22:25], v[136:139], v[34:37], v[22:25]
	s_and_b64 vcc, exec, s[12:13]
	s_cbranch_vccnz .LBB0_667
.LBB0_756:
	v_mfma_f32_16x16x32_bf16 v[26:29], v[140:143], v[34:37], v[26:29]
	s_and_b64 vcc, exec, s[14:15]
	s_cbranch_vccnz .LBB0_668
.LBB0_757:
	v_mfma_f32_16x16x32_bf16 v[30:33], v[144:147], v[34:37], v[30:33]
	s_and_b64 vcc, exec, s[16:17]
	s_cbranch_vccz .LBB0_669
	s_branch .LBB0_670
